# attention softmax subtract/scale and bias adds as packed f32 ops (pairs across rows, no op_sel)
# speedup vs baseline: 1.0117x; 1.0037x over previous
.LBB0_2544:
	s_waitcnt lgkmcnt(0)
	v_add_u32_e32 v228, s57, v153
	ds_read_b32 v158, v228
	ds_read_b32 v159, v228 offset:64
	ds_read_b128 v[116:119], v219
	ds_read_b128 v[120:123], v219 offset:64
	ds_read_b128 v[124:127], v219 offset:128
	ds_read_b128 v[128:131], v219 offset:192
	ds_read_b128 v[132:135], v219 offset:4352
	ds_read_b128 v[136:139], v219 offset:4416
	ds_read_b128 v[140:143], v219 offset:4480
	ds_read_b128 v[144:147], v219 offset:4544
	s_sub_i32 s6, s40, s41
	s_add_i32 s7, s6, -16
	s_waitcnt lgkmcnt(8)
	v_sub_u32_e32 v158, s54, v158
	v_sub_u32_e32 v159, s54, v159
	v_med3_i32 v158, v158, 0, s99
	v_med3_i32 v159, v159, 0, s99
	v_lshl_add_u32 v158, v158, 2, s98
	v_lshl_add_u32 v159, v159, 2, s98
	ds_read_b32 v158, v158
	ds_read_b32 v159, v159
	s_waitcnt lgkmcnt(9)
	v_mfma_f32_16x16x32_bf16 v[116:119], v[4:7], v[116:119], 0
	s_waitcnt lgkmcnt(5)
	v_mfma_f32_16x16x32_bf16 v[132:135], v[4:7], v[132:135], 0
	v_mfma_f32_16x16x32_bf16 v[116:119], v[8:11], v[120:123], v[116:119]
	s_waitcnt lgkmcnt(4)
	v_mfma_f32_16x16x32_bf16 v[132:135], v[8:11], v[136:139], v[132:135]
	v_mfma_f32_16x16x32_bf16 v[116:119], v[12:15], v[124:127], v[116:119]
	s_waitcnt lgkmcnt(3)
	v_mfma_f32_16x16x32_bf16 v[132:135], v[12:15], v[140:143], v[132:135]
	v_mfma_f32_16x16x32_bf16 v[116:119], v[16:19], v[128:131], v[116:119]
	s_waitcnt lgkmcnt(2)
	v_mfma_f32_16x16x32_bf16 v[132:135], v[16:19], v[144:147], v[132:135]
	s_nop 3
	s_waitcnt lgkmcnt(0)
	v_lshl_add_u32 v158, v158, 6, v191
	v_lshl_add_u32 v159, v159, 6, v191
	ds_read_b128 v[180:183], v158
	ds_read_b128 v[148:151], v159
	s_cmp_ge_i32 s6, 32
	s_waitcnt lgkmcnt(0)
	v_pk_add_f32 v[120:121], v[116:117], v[180:181]
	v_pk_add_f32 v[122:123], v[118:119], v[182:183]
	v_pk_add_f32 v[124:125], v[132:133], v[148:149]
	v_pk_add_f32 v[126:127], v[134:135], v[150:151]
	s_cbranch_scc1 .Lat_av_A
	v_cmp_gt_i32_e32 vcc, s6, v187
	v_cmp_gt_i32_e64 s[8:9], s7, v187
	s_nop 1
	v_cndmask_b32_e32 v120, v220, v120, vcc
	v_cndmask_b32_e32 v121, v220, v121, vcc
	v_cndmask_b32_e32 v122, v220, v122, vcc
	v_cndmask_b32_e32 v123, v220, v123, vcc
	v_cndmask_b32_e64 v124, v220, v124, s[8:9]
	v_cndmask_b32_e64 v125, v220, v125, s[8:9]
	v_cndmask_b32_e64 v126, v220, v126, s[8:9]
	v_cndmask_b32_e64 v127, v220, v127, s[8:9]
.Lat_av_A:
	v_max_f32_e32 v2, v120, v124
	v_max_f32_e32 v3, v121, v125
	v_max_f32_e32 v158, v122, v126
	v_max_f32_e32 v159, v123, v127
	v_max_f32_dpp v2, v2, v2 quad_perm:[1,0,3,2] row_mask:0xf bank_mask:0xf bound_ctrl:1
	v_max_f32_dpp v3, v3, v3 quad_perm:[1,0,3,2] row_mask:0xf bank_mask:0xf bound_ctrl:1
	v_max_f32_dpp v158, v158, v158 quad_perm:[1,0,3,2] row_mask:0xf bank_mask:0xf bound_ctrl:1
	v_max_f32_dpp v159, v159, v159 quad_perm:[1,0,3,2] row_mask:0xf bank_mask:0xf bound_ctrl:1
	v_max_f32_dpp v2, v2, v2 quad_perm:[2,3,0,1] row_mask:0xf bank_mask:0xf bound_ctrl:1
	v_max_f32_dpp v3, v3, v3 quad_perm:[2,3,0,1] row_mask:0xf bank_mask:0xf bound_ctrl:1
	v_max_f32_dpp v158, v158, v158 quad_perm:[2,3,0,1] row_mask:0xf bank_mask:0xf bound_ctrl:1
	v_max_f32_dpp v159, v159, v159 quad_perm:[2,3,0,1] row_mask:0xf bank_mask:0xf bound_ctrl:1
	v_max_f32_dpp v2, v2, v2 row_half_mirror row_mask:0xf bank_mask:0xf bound_ctrl:1
	v_max_f32_dpp v3, v3, v3 row_half_mirror row_mask:0xf bank_mask:0xf bound_ctrl:1
	v_max_f32_dpp v158, v158, v158 row_half_mirror row_mask:0xf bank_mask:0xf bound_ctrl:1
	v_max_f32_dpp v159, v159, v159 row_half_mirror row_mask:0xf bank_mask:0xf bound_ctrl:1
	v_mov_b32_dpp v128, v2 row_mirror row_mask:0xf bank_mask:0xf bound_ctrl:1
	v_mov_b32_dpp v129, v3 row_mirror row_mask:0xf bank_mask:0xf bound_ctrl:1
	v_mov_b32_dpp v130, v158 row_mirror row_mask:0xf bank_mask:0xf bound_ctrl:1
	v_mov_b32_dpp v131, v159 row_mirror row_mask:0xf bank_mask:0xf bound_ctrl:1
	v_max3_f32 v238, v230, v2, v128
	v_max3_f32 v239, v231, v3, v129
	v_max3_f32 v150, v232, v158, v130
	v_max3_f32 v151, v233, v159, v131
	v_pk_add_f32 v[160:161], v[230:231], v[238:239] neg_lo:[0,1] neg_hi:[0,1]
	v_pk_add_f32 v[184:185], v[232:233], v[150:151] neg_lo:[0,1] neg_hi:[0,1]
	v_pk_add_f32 v[120:121], v[120:121], v[238:239] neg_lo:[0,1] neg_hi:[0,1]
	v_pk_add_f32 v[122:123], v[122:123], v[150:151] neg_lo:[0,1] neg_hi:[0,1]
	v_pk_add_f32 v[124:125], v[124:125], v[238:239] neg_lo:[0,1] neg_hi:[0,1]
	v_pk_add_f32 v[126:127], v[126:127], v[150:151] neg_lo:[0,1] neg_hi:[0,1]
	v_mov_b64_e32 v[230:231], v[238:239]
	v_mov_b64_e32 v[232:233], v[150:151]
	v_pk_mul_f32 v[120:121], v[120:121], v[226:227]
	v_pk_mul_f32 v[122:123], v[122:123], v[226:227]
	v_pk_mul_f32 v[124:125], v[124:125], v[226:227]
	v_pk_mul_f32 v[126:127], v[126:127], v[226:227]
	v_pk_mul_f32 v[160:161], v[160:161], v[226:227]
	v_pk_mul_f32 v[184:185], v[184:185], v[226:227]
	v_exp_f32_e32 v3, v120
	v_exp_f32_e32 v159, v124
	v_exp_f32_e32 v2, v121
	v_exp_f32_e32 v158, v125
	v_exp_f32_e32 v181, v122
	v_exp_f32_e32 v183, v126
	v_exp_f32_e32 v180, v123
	v_exp_f32_e32 v182, v127
	v_exp_f32_e32 v161, v161
	v_exp_f32_e32 v160, v160
	v_exp_f32_e32 v185, v185
	v_exp_f32_e32 v184, v184
	v_cvt_pk_bf16_f32 v128, v3, v159
	v_cvt_pk_bf16_f32 v129, v2, v158
	v_cvt_pk_bf16_f32 v130, v181, v183
	v_cvt_pk_bf16_f32 v131, v180, v182
	ds_write_b16 v221, v128 offset:8704
	ds_write_b16_d16_hi v221, v128 offset:8736
	ds_write_b16 v221, v129 offset:8784
	ds_write_b16_d16_hi v221, v129 offset:8816
	ds_write_b16 v221, v130 offset:8864
	ds_write_b16_d16_hi v221, v130 offset:8896
	ds_write_b16 v221, v131 offset:8944
	ds_write_b16_d16_hi v221, v131 offset:8976
	v_min3_f32 v0, v161, v160, v185
	v_min_f32_e32 v0, v0, v184
	s_waitcnt lgkmcnt(0)
	ds_read_b128 v[116:119], v222 offset:8704
	ds_read_b64_tr_b16 v[148:149], v193 offset:0
	ds_read_b64_tr_b16 v[150:151], v193 offset:1088
	ds_read_b64_tr_b16 v[144:145], v193 offset:32
	ds_read_b64_tr_b16 v[146:147], v193 offset:1120
	ds_read_b64_tr_b16 v[140:141], v193 offset:64
	ds_read_b64_tr_b16 v[142:143], v193 offset:1152
	ds_read_b64_tr_b16 v[136:137], v193 offset:96
	ds_read_b64_tr_b16 v[138:139], v193 offset:1184
	ds_read_b64_tr_b16 v[132:133], v193 offset:128
	ds_read_b64_tr_b16 v[134:135], v193 offset:1216
	ds_read_b64_tr_b16 v[128:129], v193 offset:160
	ds_read_b64_tr_b16 v[130:131], v193 offset:1248
	ds_read_b64_tr_b16 v[124:125], v193 offset:192
	ds_read_b64_tr_b16 v[126:127], v193 offset:1280
	ds_read_b64_tr_b16 v[120:121], v193 offset:224
	ds_read_b64_tr_b16 v[122:123], v193 offset:1312
	v_cmp_neq_f32_e32 vcc, 1.0, v0
	s_cbranch_vccz .Lat_nr_A
	v_pk_mul_f32 v[60:61], v[60:61], v[160:161]
	v_pk_mul_f32 v[62:63], v[62:63], v[184:185]
	v_pk_mul_f32 v[56:57], v[56:57], v[160:161]
	v_pk_mul_f32 v[58:59], v[58:59], v[184:185]
	v_pk_mul_f32 v[52:53], v[52:53], v[160:161]
	v_pk_mul_f32 v[54:55], v[54:55], v[184:185]
	v_pk_mul_f32 v[48:49], v[48:49], v[160:161]
	v_pk_mul_f32 v[50:51], v[50:51], v[184:185]
	v_pk_mul_f32 v[44:45], v[44:45], v[160:161]
	v_pk_mul_f32 v[46:47], v[46:47], v[184:185]
	v_pk_mul_f32 v[40:41], v[40:41], v[160:161]
	v_pk_mul_f32 v[42:43], v[42:43], v[184:185]
	v_pk_mul_f32 v[36:37], v[36:37], v[160:161]
	v_pk_mul_f32 v[38:39], v[38:39], v[184:185]
	v_pk_mul_f32 v[32:33], v[32:33], v[160:161]
	v_pk_mul_f32 v[34:35], v[34:35], v[184:185]

.LBB0_2573:
	s_waitcnt lgkmcnt(0)
	ds_read_b32 v158, v228 offset:128
	ds_read_b32 v159, v228 offset:192
	ds_read_b128 v[116:119], v219
	ds_read_b128 v[120:123], v219 offset:64
	ds_read_b128 v[124:127], v219 offset:128
	ds_read_b128 v[128:131], v219 offset:192
	ds_read_b128 v[132:135], v219 offset:4352
	ds_read_b128 v[136:139], v219 offset:4416
	ds_read_b128 v[140:143], v219 offset:4480
	ds_read_b128 v[144:147], v219 offset:4544
	s_sub_i32 s6, s40, s41
	s_sub_i32 s6, s6, 32
	s_add_i32 s7, s6, -16
	s_waitcnt lgkmcnt(8)
	v_sub_u32_e32 v158, s54, v158
	v_sub_u32_e32 v159, s54, v159
	v_med3_i32 v158, v158, 0, s99
	v_med3_i32 v159, v159, 0, s99
	v_lshl_add_u32 v158, v158, 2, s98
	v_lshl_add_u32 v159, v159, 2, s98
	ds_read_b32 v158, v158
	ds_read_b32 v159, v159
	s_waitcnt lgkmcnt(9)
	v_mfma_f32_16x16x32_bf16 v[116:119], v[4:7], v[116:119], 0
	s_waitcnt lgkmcnt(5)
	v_mfma_f32_16x16x32_bf16 v[132:135], v[4:7], v[132:135], 0
	v_mfma_f32_16x16x32_bf16 v[116:119], v[8:11], v[120:123], v[116:119]
	s_waitcnt lgkmcnt(4)
	v_mfma_f32_16x16x32_bf16 v[132:135], v[8:11], v[136:139], v[132:135]
	v_mfma_f32_16x16x32_bf16 v[116:119], v[12:15], v[124:127], v[116:119]
	s_waitcnt lgkmcnt(3)
	v_mfma_f32_16x16x32_bf16 v[132:135], v[12:15], v[140:143], v[132:135]
	v_mfma_f32_16x16x32_bf16 v[116:119], v[16:19], v[128:131], v[116:119]
	s_waitcnt lgkmcnt(2)
	v_mfma_f32_16x16x32_bf16 v[132:135], v[16:19], v[144:147], v[132:135]
	s_nop 3
	s_waitcnt lgkmcnt(0)
	v_lshl_add_u32 v158, v158, 6, v191
	v_lshl_add_u32 v159, v159, 6, v191
	ds_read_b128 v[180:183], v158
	ds_read_b128 v[148:151], v159
	s_cmp_ge_i32 s6, 32
	s_waitcnt lgkmcnt(0)
	v_pk_add_f32 v[120:121], v[116:117], v[180:181]
	v_pk_add_f32 v[122:123], v[118:119], v[182:183]
	v_pk_add_f32 v[124:125], v[132:133], v[148:149]
	v_pk_add_f32 v[126:127], v[134:135], v[150:151]
	s_cbranch_scc1 .Lat_av_B
	v_cmp_gt_i32_e32 vcc, s6, v187
	v_cmp_gt_i32_e64 s[8:9], s7, v187
	s_nop 1
	v_cndmask_b32_e32 v120, v220, v120, vcc
	v_cndmask_b32_e32 v121, v220, v121, vcc
	v_cndmask_b32_e32 v122, v220, v122, vcc
	v_cndmask_b32_e32 v123, v220, v123, vcc
	v_cndmask_b32_e64 v124, v220, v124, s[8:9]
	v_cndmask_b32_e64 v125, v220, v125, s[8:9]
	v_cndmask_b32_e64 v126, v220, v126, s[8:9]
	v_cndmask_b32_e64 v127, v220, v127, s[8:9]
